# v9 with the attention-phase static priority raise on waves 0-3 instead of 4-7
# speedup vs baseline: 1.0021x; 1.0021x over previous
; #define PG8_WAIT_V(n) asm volatile("s_waitcnt vmcnt(" #n ")" ::: "memory")
; #define PG8_BAR __builtin_amdgcn_s_barrier()
; #define LAS __attribute__((address_space(3)))
; template <class Epi, class Sched, bool ALIGN_EPI = false, bool SP2 = false>
; __device__ __forceinline__ void gemm_phase(PG8_LAS unsigned char* lds, const Gemm g, const Sched& S, const Epi& E) {
;     ...
;     PG8_WAIT_V(0);
;     if constexpr (!ALIGN_EPI) { if (wr == 0) PG8_BAR; }
;     PG8_BAR;
; __device__ __forceinline__ void ab_phase(const h16* H, const float* sinks, h16* Y, h16* PO16, float* LSE, LAS unsigned char* lds, int G) {
;     constexpr int SLOT = 9216, VP = 144, NU = 2560;
;     int tid = threadIdx.x; asm volatile("" : "+v"(tid));
;     const int lane = tid & 63, w = __builtin_amdgcn_readfirstlane(tid >> 6), r32 = lane & 31, hi = lane >> 5;
;     const int isV = tid >> 8, lrow = (tid & 255) >> 3, lcc = tid & 7;
;     const int q4 = (lane & 15) >> 2, p4 = lane & 3, dblk = (lane >> 4) & 1;
;     const int vrd_off = (4 * hi + q4) * VP + dblk * 32 + p4 * 8;
;     LAS unsigned char* wdst = lds + (isV ? 0 : 32 * VP) + lrow * VP + lcc * 16;
;     u32x4 tr[12]; h8 qn[4];
;     ...
;     int U = ((gridDim.x % 8 == 0) ? (int)((blockIdx.x % 8) * (gridDim.x / 8) + blockIdx.x / 8) : (int)blockIdx.x);
;     if (U < NU) AB_ISSUE(U);
;     for (; U < NU; U += G) {
.LBB0_205:
	s_or_b64 exec, exec, s[0:1]
	s_and_b32 s0, s84, 7
	s_cmp_eq_u32 s0, 0
	s_mov_b64 s[8:9], s[78:79]
	s_mov_b64 s[44:45], s[76:77]
	s_waitcnt lgkmcnt(0)
	v_mov_b32_e32 v0, v204
	s_setprio 0
	v_mov_b32_e32 v5, v204
	s_cselect_b64 s[4:5], -1, 0
	s_barrier
	v_readfirstlane_b32 s98, v204
	s_lshr_b32 s98, s98, 8
	s_cmp_lg_u32 s98, 0
	s_cbranch_scc1 .Laprio_skip_p2
	s_setprio 1

; #define PG8_WAIT_V(n) asm volatile("s_waitcnt vmcnt(" #n ")" ::: "memory")
; #define PG8_BAR __builtin_amdgcn_s_barrier()
; #define LAS __attribute__((address_space(3)))
; template <class Epi, class Sched, bool ALIGN_EPI = false, bool SP2 = false>
; __device__ __forceinline__ void gemm_phase(PG8_LAS unsigned char* lds, const Gemm g, const Sched& S, const Epi& E) {
;     ...
;     PG8_WAIT_V(0);
;     if constexpr (!ALIGN_EPI) { if (wr == 0) PG8_BAR; }
;     PG8_BAR;
; __device__ __forceinline__ void ab_phase(const h16* H, const float* sinks, h16* Y, h16* PO16, float* LSE, LAS unsigned char* lds, int G) {
;     constexpr int SLOT = 9216, VP = 144, NU = 2560;
;     int tid = threadIdx.x; asm volatile("" : "+v"(tid));
;     const int lane = tid & 63, w = __builtin_amdgcn_readfirstlane(tid >> 6), r32 = lane & 31, hi = lane >> 5;
;     const int isV = tid >> 8, lrow = (tid & 255) >> 3, lcc = tid & 7;
;     const int q4 = (lane & 15) >> 2, p4 = lane & 3, dblk = (lane >> 4) & 1;
.LBB0_806:
	s_or_b64 exec, exec, s[0:1]
	s_mov_b64 s[10:11], s[78:79]
	s_mov_b64 s[0:1], s[76:77]
	s_waitcnt lgkmcnt(0)
	s_barrier
	v_mov_b32_e32 v0, v204
	s_setprio 0
	v_readfirstlane_b32 s98, v204
	s_lshr_b32 s98, s98, 8
	s_cmp_lg_u32 s98, 0
	s_cbranch_scc1 .Laprio_skip_0
	s_setprio 1

; #define PG8_WAIT_V(n) asm volatile("s_waitcnt vmcnt(" #n ")" ::: "memory")
; #define PG8_BAR __builtin_amdgcn_s_barrier()
; #define LAS __attribute__((address_space(3)))
; template <class Epi, class Sched, bool ALIGN_EPI = false, bool SP2 = false>
; __device__ __forceinline__ void gemm_phase(PG8_LAS unsigned char* lds, const Gemm g, const Sched& S, const Epi& E) {
;     ...
;     PG8_WAIT_V(0);
;     if constexpr (!ALIGN_EPI) { if (wr == 0) PG8_BAR; }
;     PG8_BAR;
; __device__ __forceinline__ void ab_phase(const h16* H, const float* sinks, h16* Y, h16* PO16, float* LSE, LAS unsigned char* lds, int G) {
;     constexpr int SLOT = 9216, VP = 144, NU = 2560;
;     int tid = threadIdx.x; asm volatile("" : "+v"(tid));
;     const int lane = tid & 63, w = __builtin_amdgcn_readfirstlane(tid >> 6), r32 = lane & 31, hi = lane >> 5;
;     const int isV = tid >> 8, lrow = (tid & 255) >> 3, lcc = tid & 7;
;     const int q4 = (lane & 15) >> 2, p4 = lane & 3, dblk = (lane >> 4) & 1;
.LBB0_955:
	s_or_b64 exec, exec, s[0:1]
	s_mov_b64 s[48:49], s[78:79]
	s_mov_b64 s[0:1], s[76:77]
	s_waitcnt lgkmcnt(0)
	s_barrier
	v_mov_b32_e32 v0, v204
	s_setprio 0
	v_readfirstlane_b32 s98, v204
	s_lshr_b32 s98, s98, 8
	s_cmp_lg_u32 s98, 0
	s_cbranch_scc1 .Laprio_skip_1
	s_setprio 1

; #define LAS __attribute__((address_space(3)))
; __device__ __forceinline__ void ab_phase(const h16* H, const float* sinks, h16* Y, h16* PO16, float* LSE, LAS unsigned char* lds, int G) {
;     constexpr int SLOT = 9216, VP = 144, NU = 2560;
;     int tid = threadIdx.x; asm volatile("" : "+v"(tid));
;     const int lane = tid & 63, w = __builtin_amdgcn_readfirstlane(tid >> 6), r32 = lane & 31, hi = lane >> 5;
;     const int isV = tid >> 8, lrow = (tid & 255) >> 3, lcc = tid & 7;
;     const int q4 = (lane & 15) >> 2, p4 = lane & 3, dblk = (lane >> 4) & 1;
.LBB0_967:
	v_readlane_b32 s0, v234, 6
	v_mov_b32_e32 v0, v204
	s_setprio 0
	v_readfirstlane_b32 s98, v204
	s_lshr_b32 s98, s98, 8
	s_cmp_lg_u32 s98, 0
	s_cbranch_scc1 .Laprio_skip_2
	s_setprio 1
